# strategy 7.4 over the whole chunk precompute (p3a): static s_setprio 1 for waves 4-7 from p3a entry to exit (the two waves of each SIMD run out of phase in every stage)
# baseline (speedup 1.0000x reference)
.LBB0_489:
	v_readlane_b32 s5, v249, 49
	s_nop 0
	s_cmp_ge_u32 s5, 4
	s_cbranch_scc0 .Lp3a_noprio
	s_setprio 1
.Lp3a_noprio:
	s_lshl_b32 s0, s5, 1
	s_and_b32 s16, s0, 0x7fffff8
	s_lshl_b32 s0, s5, 11
	s_add_i32 s0, s0, 0
	s_lshl_b32 s1, s5, 3
	v_writelane_b32 v249, s0, 54
	v_writelane_b32 v249, s1, 55
	s_add_i32 s0, s1, -3
	v_writelane_b32 v249, s0, 56
	s_and_b32 s8, s1, 24
	v_readlane_b32 s4, v249, 4
	s_cmpk_lt_u32 s4, 0x80
	s_cselect_b64 s[96:97], -1, 0
	s_and_b32 s0, s4, 64
	s_bfe_u32 s2, s4, 0x20006
	s_cmp_lg_u32 s2, 3
	s_cselect_b64 s[28:29], -1, 0
	s_cmpk_lt_u32 s4, 0x100
	v_writelane_b32 v249, s0, 57
	s_cselect_b64 s[0:1], -1, 0
	v_writelane_b32 v249, s0, 58
	s_cmp_lg_u32 s2, 0
	s_mov_b32 s41, 0
	v_writelane_b32 v249, s1, 59
	s_cselect_b64 s[0:1], -1, 0
	v_cndmask_b32_e64 v2, 0, 1, s[0:1]
	s_and_b64 s[0:1], s[0:1], exec
	s_cselect_b32 s3, 0x2000, 0
	s_cmp_eq_u32 s2, 2
	s_cselect_b64 s[0:1], -1, 0
	v_cndmask_b32_e64 v3, 0, 1, s[0:1]
	s_and_b64 s[0:1], s[0:1], exec
	s_cselect_b32 s2, 0x2000, 0
	s_cmpk_gt_u32 s4, 0xff
	s_cselect_b64 s[20:21], -1, 0
	s_and_b64 s[0:1], s[20:21], exec
	v_readfirstlane_b32 s0, v3
	v_readfirstlane_b32 s1, v2
	s_cselect_b32 s4, s0, s1
	s_cselect_b32 s0, s1, s0
	s_and_b32 s1, 1, s4
	s_bitcmp1_b32 s0, 0
	s_cselect_b32 s0, 32, 0
	v_writelane_b32 v249, s0, 60
	s_cselect_b32 s0, 2, 0
	s_cmp_eq_u32 s1, 1
	s_cselect_b32 s4, 32, 0
	v_writelane_b32 v249, s4, 61
	s_cselect_b32 s4, 2, 0
	s_cselect_b32 s1, 0x2000, 0
	s_add_i32 s0, s0, s4
	s_lshl_b32 s4, s0, 10
	s_lshl_b32 s0, s0, 6
	s_or_b32 s0, s0, 64
	v_writelane_b32 v249, s4, 62
	s_cmp_lg_u32 s5, 3
	v_writelane_b32 v249, s0, 63
	s_cselect_b64 s[6:7], -1, 0
	s_mul_i32 s0, s5, 0x2100
	v_writelane_b32 v248, s6, 0
	s_add_i32 s0, s0, 0
	s_add_i32 s0, s0, 0x10000
	v_writelane_b32 v248, s7, 1
	v_writelane_b32 v248, s0, 2
	s_or_b32 s4, s8, 1
	v_writelane_b32 v248, s4, 3
	s_or_b32 s4, s8, 2
	v_writelane_b32 v248, s4, 4
	s_or_b32 s4, s8, 3
	v_writelane_b32 v248, s4, 5
	s_or_b32 s4, s8, 4
	v_writelane_b32 v248, s4, 6
	s_or_b32 s4, s8, 5
	v_writelane_b32 v248, s4, 7
	s_or_b32 s4, s8, 6
	v_writelane_b32 v248, s4, 8
	v_writelane_b32 v248, s8, 9
	s_or_b32 s4, s8, 7
	v_writelane_b32 v248, s4, 10
	s_add_i32 s1, s1, 0
	v_writelane_b32 v248, s1, 11
	s_add_i32 s1, s2, 0
	s_lshl_b32 s0, s5, 8
	v_writelane_b32 v248, s1, 12
	s_add_i32 s1, s3, 0
	v_writelane_b32 v248, s1, 13
	s_add_u32 s1, s70, 0x8000
	v_writelane_b32 v248, s1, 14
	s_addc_u32 s1, s71, 0
	v_writelane_b32 v248, s1, 15
	v_mbcnt_lo_u32_b32 v2, -1, 0
	s_add_i32 s1, 0, 0xc000
	s_add_i32 s0, s0, 0
	v_mbcnt_hi_u32_b32 v184, -1, v2
	v_writelane_b32 v248, s1, 16
	s_add_i32 s0, s0, 0x20800
	v_bfrev_b32_e32 v2, 0.5
	v_writelane_b32 v248, s0, 17
	s_mov_b32 s48, 0x800000
	s_add_i32 s49, 0, 0x4000
	s_movk_i32 s65, 0x200
	s_waitcnt vmcnt(3)
	v_mov_b32_e32 v18, 0
	v_mov_b32_e32 v185, 0x3ecc95a3
	s_mov_b32 s17, 0x24300000
	v_mov_b32_e32 v186, 1
	v_mov_b32_e32 v187, 0x3db504f3
	v_mov_b32_e32 v188, 0x7fff8000
	v_mov_b32_e32 v158, 0x3f317218
	v_mov_b32_e32 v189, 0x7f800000
	v_mov_b32_e32 v190, 0x7fc00000
	v_mov_b32_e32 v191, 0xff800000
	v_lshl_or_b32 v192, v184, 2, v2
	v_mov_b32_e32 v193, 0x800
	s_mov_b32 s8, 0
	v_writelane_b32 v248, s81, 18
	s_mov_b32 s33, 0x24300000
	v_writelane_b32 v248, s10, 19
	s_branch .LBB0_491

.LBB0_658:
	s_setprio 0
	v_readlane_b32 s0, v249, 7
	s_cmp_gt_i32 s0, 63
	s_mov_b64 s[0:1], -1
	s_cbranch_scc0 .LBB0_772
	v_readlane_b32 s2, v249, 51
	s_cmp_gt_i32 s2, 19
	s_cbranch_scc0 .LBB0_663
	s_lshl_b32 s0, s2, 1
	s_sub_i32 s1, s0, 28
	s_cmp_lt_u32 s2, 28
	s_cselect_b32 s33, 2, 1
	s_cselect_b32 s31, s1, s2
	s_cmp_lt_i32 s2, 21
	s_mov_b32 s30, 12
	s_cbranch_scc1 .LBB0_667
	v_readlane_b32 s1, v249, 51
	s_cmp_eq_u32 s1, 21
	s_cbranch_scc1 .LBB0_664
	s_add_i32 s30, s0, -4
	s_mov_b64 s[0:1], 0
	s_branch .LBB0_665
